# SGPR-base LDS-DMA addressing also in the in-proj, out-proj and down-proj K-loops
# baseline (speedup 1.0000x reference)
.LBB0_118:
	ds_read_b128 v[128:131], v207
	ds_read_b128 v[132:135], v207 offset:1024
	ds_read_b128 v[136:139], v207 offset:2048
	ds_read_b128 v[140:143], v207 offset:3072
	s_waitcnt lgkmcnt(0)
	ds_read_b128 v[162:165], v208
	ds_read_b128 v[170:173], v208 offset:1024
	ds_read_b128 v[174:177], v208 offset:2048
	ds_read_b128 v[178:181], v208 offset:3072
	s_add_u32 s18, s58, 0xfffc0080
	s_addc_u32 s19, s59, -1
	s_cmp_eq_u32 s55, 12
	s_cselect_b32 s63, s0, s19
	s_cselect_b32 s62, s1, s18
	s_cselect_b32 s61, s3, s49
	s_cselect_b32 s60, s33, s47
	s_add_i32 m0, s57, 0xc000
	ds_read_b128 v[182:185], v209
	ds_read_b128 v[186:189], v209 offset:1024
	ds_read_b128 v[190:193], v209 offset:2048
	ds_read_b128 v[194:197], v209 offset:3072
	ds_read_b128 v[198:201], v209 offset:4096
	ds_read_b128 v[212:215], v209 offset:5120
	ds_read_b128 v[216:219], v209 offset:6144
	ds_read_b128 v[220:223], v209 offset:7168
	global_load_lds_dwordx4 v154, s[58:59]
	s_add_i32 m0, s57, 0xe000
	s_nop 0
	global_load_lds_dwordx4 v156, s[58:59]
	s_waitcnt vmcnt(8)
	s_waitcnt lgkmcnt(0)
	s_barrier
	s_setprio 1
	s_waitcnt lgkmcnt(0)
	v_mfma_f32_16x16x32_bf16 v[124:127], v[128:131], v[182:185], v[124:127]
	v_mfma_f32_16x16x32_bf16 v[120:123], v[136:139], v[182:185], v[120:123]
	v_mfma_f32_16x16x32_bf16 v[116:119], v[128:131], v[190:193], v[116:119]
	v_mfma_f32_16x16x32_bf16 v[112:115], v[136:139], v[190:193], v[112:115]
	v_mfma_f32_16x16x32_bf16 v[108:111], v[128:131], v[198:201], v[108:111]
	v_mfma_f32_16x16x32_bf16 v[104:107], v[136:139], v[198:201], v[104:107]
	v_mfma_f32_16x16x32_bf16 v[100:103], v[128:131], v[216:219], v[100:103]
	v_mfma_f32_16x16x32_bf16 v[96:99], v[136:139], v[216:219], v[96:99]
	v_mfma_f32_16x16x32_bf16 v[124:127], v[132:135], v[186:189], v[124:127]
	v_mfma_f32_16x16x32_bf16 v[120:123], v[140:143], v[186:189], v[120:123]
	v_mfma_f32_16x16x32_bf16 v[116:119], v[132:135], v[194:197], v[116:119]
	v_mfma_f32_16x16x32_bf16 v[112:115], v[140:143], v[194:197], v[112:115]
	v_mfma_f32_16x16x32_bf16 v[108:111], v[132:135], v[212:215], v[108:111]
	v_mfma_f32_16x16x32_bf16 v[104:107], v[140:143], v[212:215], v[104:107]
	v_mfma_f32_16x16x32_bf16 v[100:103], v[132:135], v[220:223], v[100:103]
	v_mfma_f32_16x16x32_bf16 v[96:99], v[140:143], v[220:223], v[96:99]
	s_setprio 0
	s_setprio 1
	v_mfma_f32_16x16x32_bf16 v[68:71], v[162:165], v[182:185], v[68:71]
	v_mfma_f32_16x16x32_bf16 v[64:67], v[174:177], v[182:185], v[64:67]
	v_mfma_f32_16x16x32_bf16 v[52:55], v[162:165], v[190:193], v[52:55]
	v_mfma_f32_16x16x32_bf16 v[48:51], v[174:177], v[190:193], v[48:51]
	v_mfma_f32_16x16x32_bf16 v[44:47], v[162:165], v[198:201], v[44:47]
	v_mfma_f32_16x16x32_bf16 v[40:43], v[174:177], v[198:201], v[40:43]
	v_mfma_f32_16x16x32_bf16 v[36:39], v[162:165], v[216:219], v[36:39]
	v_mfma_f32_16x16x32_bf16 v[32:35], v[174:177], v[216:219], v[32:35]
	v_mfma_f32_16x16x32_bf16 v[68:71], v[170:173], v[186:189], v[68:71]
	v_mfma_f32_16x16x32_bf16 v[64:67], v[178:181], v[186:189], v[64:67]
	v_mfma_f32_16x16x32_bf16 v[52:55], v[170:173], v[194:197], v[52:55]
	v_mfma_f32_16x16x32_bf16 v[48:51], v[178:181], v[194:197], v[48:51]
	v_mfma_f32_16x16x32_bf16 v[44:47], v[170:173], v[212:215], v[44:47]
	v_mfma_f32_16x16x32_bf16 v[40:43], v[178:181], v[212:215], v[40:43]
	v_mfma_f32_16x16x32_bf16 v[36:39], v[170:173], v[220:223], v[36:39]
	v_mfma_f32_16x16x32_bf16 v[32:35], v[178:181], v[220:223], v[32:35]
	s_setprio 0
	s_barrier
	s_add_i32 s18, s88, s66
	s_mov_b32 m0, s18
	ds_read_b128 v[182:185], v209 offset:16384
	ds_read_b128 v[186:189], v209 offset:17408
	ds_read_b128 v[190:193], v209 offset:18432
	ds_read_b128 v[194:197], v209 offset:19456
	ds_read_b128 v[198:201], v209 offset:20480
	ds_read_b128 v[212:215], v209 offset:21504
	ds_read_b128 v[216:219], v209 offset:22528
	ds_read_b128 v[220:223], v209 offset:23552
	global_load_lds_dwordx4 v146, s[60:61]
	s_add_i32 m0, s18, 0x2000
	s_add_u32 s18, s60, 0x40000
	s_addc_u32 s19, s61, 0
	s_add_i32 s36, s89, s66
	global_load_lds_dwordx4 v150, s[60:61]
	s_mov_b32 m0, s36
	s_nop 0
	global_load_lds_dwordx4 v146, s[18:19]
	s_add_i32 m0, s36, 0x2000
	s_nop 0
	global_load_lds_dwordx4 v150, s[18:19]
	s_add_u32 vcc_lo, s62, s22
	s_addc_u32 vcc_hi, s63, s23
	s_mov_b32 m0, s57
	s_nop 0
	global_load_lds_dwordx4 v144, s[62:63]
	s_mov_b32 m0, s67
	s_nop 0
	global_load_lds_dwordx4 v148, s[62:63]
	s_waitcnt vmcnt(8)
	s_waitcnt lgkmcnt(0)
	s_barrier
	s_setprio 1
	s_waitcnt lgkmcnt(0)
	v_mfma_f32_16x16x32_bf16 v[92:95], v[128:131], v[182:185], v[92:95]
	v_mfma_f32_16x16x32_bf16 v[88:91], v[136:139], v[182:185], v[88:91]
	v_mfma_f32_16x16x32_bf16 v[84:87], v[128:131], v[190:193], v[84:87]
	v_mfma_f32_16x16x32_bf16 v[80:83], v[136:139], v[190:193], v[80:83]
	v_mfma_f32_16x16x32_bf16 v[76:79], v[128:131], v[198:201], v[76:79]
	v_mfma_f32_16x16x32_bf16 v[72:75], v[136:139], v[198:201], v[72:75]
	v_mfma_f32_16x16x32_bf16 v[60:63], v[128:131], v[216:219], v[60:63]
	v_mfma_f32_16x16x32_bf16 v[56:59], v[136:139], v[216:219], v[56:59]
	v_mfma_f32_16x16x32_bf16 v[92:95], v[132:135], v[186:189], v[92:95]
	v_mfma_f32_16x16x32_bf16 v[88:91], v[140:143], v[186:189], v[88:91]
	v_mfma_f32_16x16x32_bf16 v[84:87], v[132:135], v[194:197], v[84:87]
	v_mfma_f32_16x16x32_bf16 v[80:83], v[140:143], v[194:197], v[80:83]
	v_mfma_f32_16x16x32_bf16 v[76:79], v[132:135], v[212:215], v[76:79]
	v_mfma_f32_16x16x32_bf16 v[72:75], v[140:143], v[212:215], v[72:75]
	v_mfma_f32_16x16x32_bf16 v[60:63], v[132:135], v[220:223], v[60:63]
	v_mfma_f32_16x16x32_bf16 v[56:59], v[140:143], v[220:223], v[56:59]
	s_setprio 0
	s_setprio 1
	v_mfma_f32_16x16x32_bf16 v[28:31], v[162:165], v[182:185], v[28:31]
	v_mfma_f32_16x16x32_bf16 v[24:27], v[174:177], v[182:185], v[24:27]
	v_mfma_f32_16x16x32_bf16 v[20:23], v[162:165], v[190:193], v[20:23]
	v_mfma_f32_16x16x32_bf16 v[16:19], v[174:177], v[190:193], v[16:19]
	v_mfma_f32_16x16x32_bf16 v[12:15], v[162:165], v[198:201], v[12:15]
	v_mfma_f32_16x16x32_bf16 v[8:11], v[174:177], v[198:201], v[8:11]
	v_mfma_f32_16x16x32_bf16 v[4:7], v[162:165], v[216:219], v[4:7]
	v_mfma_f32_16x16x32_bf16 v[0:3], v[174:177], v[216:219], v[0:3]
	v_mfma_f32_16x16x32_bf16 v[28:31], v[170:173], v[186:189], v[28:31]
	v_mfma_f32_16x16x32_bf16 v[24:27], v[178:181], v[186:189], v[24:27]
	v_mfma_f32_16x16x32_bf16 v[20:23], v[170:173], v[194:197], v[20:23]
	v_mfma_f32_16x16x32_bf16 v[16:19], v[178:181], v[194:197], v[16:19]
	v_mfma_f32_16x16x32_bf16 v[12:15], v[170:173], v[212:215], v[12:15]
	v_mfma_f32_16x16x32_bf16 v[8:11], v[178:181], v[212:215], v[8:11]
	v_mfma_f32_16x16x32_bf16 v[4:7], v[170:173], v[220:223], v[4:7]
	v_mfma_f32_16x16x32_bf16 v[0:3], v[178:181], v[220:223], v[0:3]
	s_setprio 0
	s_barrier
	s_add_i32 s36, 0, 0x18000
	s_add_i32 s37, 0, 0x1c000
	v_add_u32_e32 v140, s36, v204
	v_add_u32_e32 v152, s37, v204
	ds_read_b128 v[128:131], v140
	ds_read_b128 v[132:135], v140 offset:1024
	ds_read_b128 v[136:139], v140 offset:2048
	ds_read_b128 v[140:143], v140 offset:3072
	ds_read_b128 v[162:165], v152
	ds_read_b128 v[170:173], v152 offset:1024
	ds_read_b128 v[174:177], v152 offset:2048
	ds_read_b128 v[178:181], v152 offset:3072
	s_add_u32 s18, s62, 0x40000
	s_addc_u32 s19, s63, 0
	s_mov_b32 m0, s68
	ds_read_b128 v[182:185], v209 offset:32768
	ds_read_b128 v[186:189], v209 offset:33792
	ds_read_b128 v[190:193], v209 offset:34816
	ds_read_b128 v[194:197], v209 offset:35840
	ds_read_b128 v[198:201], v209 offset:36864
	ds_read_b128 v[212:215], v209 offset:37888
	ds_read_b128 v[216:219], v209 offset:38912
	ds_read_b128 v[220:223], v209 offset:39936
	global_load_lds_dwordx4 v144, s[18:19]
	s_mov_b32 m0, s69
	s_nop 0
	global_load_lds_dwordx4 v148, s[18:19]
	s_waitcnt vmcnt(8)
	s_waitcnt lgkmcnt(0)
	s_barrier
	s_setprio 1
	s_waitcnt lgkmcnt(0)
	v_mfma_f32_16x16x32_bf16 v[124:127], v[128:131], v[182:185], v[124:127]
	v_mfma_f32_16x16x32_bf16 v[120:123], v[136:139], v[182:185], v[120:123]
	v_mfma_f32_16x16x32_bf16 v[116:119], v[128:131], v[190:193], v[116:119]
	v_mfma_f32_16x16x32_bf16 v[112:115], v[136:139], v[190:193], v[112:115]
	v_mfma_f32_16x16x32_bf16 v[108:111], v[128:131], v[198:201], v[108:111]
	v_mfma_f32_16x16x32_bf16 v[104:107], v[136:139], v[198:201], v[104:107]
	v_mfma_f32_16x16x32_bf16 v[100:103], v[128:131], v[216:219], v[100:103]
	v_mfma_f32_16x16x32_bf16 v[96:99], v[136:139], v[216:219], v[96:99]
	v_mfma_f32_16x16x32_bf16 v[124:127], v[132:135], v[186:189], v[124:127]
	v_mfma_f32_16x16x32_bf16 v[120:123], v[140:143], v[186:189], v[120:123]
	v_mfma_f32_16x16x32_bf16 v[116:119], v[132:135], v[194:197], v[116:119]
	v_mfma_f32_16x16x32_bf16 v[112:115], v[140:143], v[194:197], v[112:115]
	v_mfma_f32_16x16x32_bf16 v[108:111], v[132:135], v[212:215], v[108:111]
	v_mfma_f32_16x16x32_bf16 v[104:107], v[140:143], v[212:215], v[104:107]
	v_mfma_f32_16x16x32_bf16 v[100:103], v[132:135], v[220:223], v[100:103]
	v_mfma_f32_16x16x32_bf16 v[96:99], v[140:143], v[220:223], v[96:99]
	s_setprio 0
	s_setprio 1
	v_mfma_f32_16x16x32_bf16 v[68:71], v[162:165], v[182:185], v[68:71]
	v_mfma_f32_16x16x32_bf16 v[64:67], v[174:177], v[182:185], v[64:67]
	v_mfma_f32_16x16x32_bf16 v[52:55], v[162:165], v[190:193], v[52:55]
	v_mfma_f32_16x16x32_bf16 v[48:51], v[174:177], v[190:193], v[48:51]
	v_mfma_f32_16x16x32_bf16 v[44:47], v[162:165], v[198:201], v[44:47]
	v_mfma_f32_16x16x32_bf16 v[40:43], v[174:177], v[198:201], v[40:43]
	v_mfma_f32_16x16x32_bf16 v[36:39], v[162:165], v[216:219], v[36:39]
	v_mfma_f32_16x16x32_bf16 v[32:35], v[174:177], v[216:219], v[32:35]
	v_mfma_f32_16x16x32_bf16 v[68:71], v[170:173], v[186:189], v[68:71]
	v_mfma_f32_16x16x32_bf16 v[64:67], v[178:181], v[186:189], v[64:67]
	v_mfma_f32_16x16x32_bf16 v[52:55], v[170:173], v[194:197], v[52:55]
	v_mfma_f32_16x16x32_bf16 v[48:51], v[178:181], v[194:197], v[48:51]
	v_mfma_f32_16x16x32_bf16 v[44:47], v[170:173], v[212:215], v[44:47]
	v_mfma_f32_16x16x32_bf16 v[40:43], v[178:181], v[212:215], v[40:43]
	v_mfma_f32_16x16x32_bf16 v[36:39], v[170:173], v[220:223], v[36:39]
	v_mfma_f32_16x16x32_bf16 v[32:35], v[178:181], v[220:223], v[32:35]
	s_setprio 0
	s_barrier
	s_add_i32 s18, s36, s66
	s_add_u32 s98, s60, s22
	s_addc_u32 s99, s61, s23
	s_mov_b32 m0, s18
	ds_read_b128 v[182:185], v209 offset:49152
	ds_read_b128 v[186:189], v209 offset:50176
	ds_read_b128 v[190:193], v209 offset:51200
	ds_read_b128 v[194:197], v209 offset:52224
	ds_read_b128 v[198:201], v209 offset:53248
	ds_read_b128 v[212:215], v209 offset:54272
	ds_read_b128 v[216:219], v209 offset:55296
	ds_read_b128 v[220:223], v209 offset:56320
	global_load_lds_dwordx4 v146, s[98:99]
	s_add_i32 m0, s18, 0x2000
	s_add_u32 s18, s60, 0x40080
	s_addc_u32 s19, s61, 0
	s_add_i32 s36, s37, s66
	global_load_lds_dwordx4 v150, s[98:99]
	s_mov_b32 m0, s36
	s_nop 0
	global_load_lds_dwordx4 v146, s[18:19]
	s_add_i32 m0, s36, 0x2000
	s_nop 0
	global_load_lds_dwordx4 v150, s[18:19]
	s_mov_b32 m0, s82
	s_nop 0
	global_load_lds_dwordx4 v144, vcc
	s_mov_b32 m0, s83
	s_nop 0
	global_load_lds_dwordx4 v148, vcc
	s_waitcnt vmcnt(8)
	s_waitcnt lgkmcnt(0)
	s_barrier
	s_setprio 1
	s_waitcnt lgkmcnt(0)
	v_mfma_f32_16x16x32_bf16 v[92:95], v[128:131], v[182:185], v[92:95]
	v_mfma_f32_16x16x32_bf16 v[88:91], v[136:139], v[182:185], v[88:91]
	v_mfma_f32_16x16x32_bf16 v[84:87], v[128:131], v[190:193], v[84:87]
	v_mfma_f32_16x16x32_bf16 v[80:83], v[136:139], v[190:193], v[80:83]
	v_mfma_f32_16x16x32_bf16 v[76:79], v[128:131], v[198:201], v[76:79]
	v_mfma_f32_16x16x32_bf16 v[72:75], v[136:139], v[198:201], v[72:75]
	v_mfma_f32_16x16x32_bf16 v[60:63], v[128:131], v[216:219], v[60:63]
	v_mfma_f32_16x16x32_bf16 v[56:59], v[136:139], v[216:219], v[56:59]
	v_mfma_f32_16x16x32_bf16 v[92:95], v[132:135], v[186:189], v[92:95]
	v_mfma_f32_16x16x32_bf16 v[88:91], v[140:143], v[186:189], v[88:91]
	v_mfma_f32_16x16x32_bf16 v[84:87], v[132:135], v[194:197], v[84:87]
	v_mfma_f32_16x16x32_bf16 v[80:83], v[140:143], v[194:197], v[80:83]
	v_mfma_f32_16x16x32_bf16 v[76:79], v[132:135], v[212:215], v[76:79]
	v_mfma_f32_16x16x32_bf16 v[72:75], v[140:143], v[212:215], v[72:75]
	v_mfma_f32_16x16x32_bf16 v[60:63], v[132:135], v[220:223], v[60:63]
	v_mfma_f32_16x16x32_bf16 v[56:59], v[140:143], v[220:223], v[56:59]
	s_setprio 0
	s_setprio 1
	v_mfma_f32_16x16x32_bf16 v[28:31], v[162:165], v[182:185], v[28:31]
	v_mfma_f32_16x16x32_bf16 v[24:27], v[174:177], v[182:185], v[24:27]
	v_mfma_f32_16x16x32_bf16 v[20:23], v[162:165], v[190:193], v[20:23]
	v_mfma_f32_16x16x32_bf16 v[16:19], v[174:177], v[190:193], v[16:19]
	v_mfma_f32_16x16x32_bf16 v[12:15], v[162:165], v[198:201], v[12:15]
	v_mfma_f32_16x16x32_bf16 v[8:11], v[174:177], v[198:201], v[8:11]
	v_mfma_f32_16x16x32_bf16 v[4:7], v[162:165], v[216:219], v[4:7]
	v_mfma_f32_16x16x32_bf16 v[0:3], v[174:177], v[216:219], v[0:3]
	v_mfma_f32_16x16x32_bf16 v[28:31], v[170:173], v[186:189], v[28:31]
	v_mfma_f32_16x16x32_bf16 v[24:27], v[178:181], v[186:189], v[24:27]
	v_mfma_f32_16x16x32_bf16 v[20:23], v[170:173], v[194:197], v[20:23]
	v_mfma_f32_16x16x32_bf16 v[16:19], v[178:181], v[194:197], v[16:19]
	v_mfma_f32_16x16x32_bf16 v[12:15], v[170:173], v[212:215], v[12:15]
	v_mfma_f32_16x16x32_bf16 v[8:11], v[178:181], v[212:215], v[8:11]
	v_mfma_f32_16x16x32_bf16 v[4:7], v[170:173], v[220:223], v[4:7]
	v_mfma_f32_16x16x32_bf16 v[0:3], v[178:181], v[220:223], v[0:3]
	s_setprio 0
	s_barrier
	s_add_i32 s55, s55, 2
	s_add_u32 s58, s58, 0x100
	s_addc_u32 s59, s59, 0
	s_add_u32 s47, s47, 0x100
	s_addc_u32 s49, s49, 0
	s_cmp_gt_u32 s55, 13
	s_cbranch_scc0 .LBB0_118
	s_and_b64 vcc, exec, s[10:11]
	s_cbranch_vccz .LBB0_121
	s_barrier

.LBB0_449:
	v_add_u32_e32 v1, s72, v149
	ds_read_b128 v[158:161], v1
	s_waitcnt lgkmcnt(0)
	ds_read_b128 v[162:165], v1 offset:1024
	ds_read_b128 v[170:173], v1 offset:2048
	ds_read_b128 v[174:177], v1 offset:3072
	v_add_u32_e32 v1, s73, v149
	s_add_u32 s58, s54, s56
	ds_read_b128 v[178:181], v1
	ds_read_b128 v[182:185], v1 offset:1024
	ds_read_b128 v[186:189], v1 offset:2048
	ds_read_b128 v[190:193], v1 offset:3072
	s_addc_u32 s59, s55, s57
	s_add_u32 s58, s58, 0x100
	s_addc_u32 s59, s59, 0
	s_add_u32 s78, s75, s56
	s_addc_u32 s79, s76, s57
	s_cmpk_eq_i32 s56, 0x700
	s_cselect_b32 s61, s33, s59
	s_cselect_b32 s60, s43, s58
	s_cselect_b32 s59, s45, s79
	s_cselect_b32 s58, s51, s78
	v_lshl_add_u64 v[2:3], v[144:145], 0, s[56:57]
	s_add_i32 m0, s53, 0xc000
	ds_read_b128 v[194:197], v154
	ds_read_b128 v[198:201], v154 offset:1024
	ds_read_b128 v[202:205], v154 offset:2048
	ds_read_b128 v[206:209], v154 offset:3072
	ds_read_b128 v[210:213], v154 offset:4096
	ds_read_b128 v[214:217], v154 offset:5120
	ds_read_b128 v[218:221], v154 offset:6144
	ds_read_b128 v[222:225], v154 offset:7168
	global_load_lds_dwordx4 v[2:3], off
	v_lshl_add_u64 v[2:3], v[146:147], 0, s[56:57]
	s_add_i32 m0, s53, 0xe000
	s_nop 0
	global_load_lds_dwordx4 v[2:3], off
	s_waitcnt vmcnt(8)
	s_waitcnt lgkmcnt(0)
	s_barrier
	s_setprio 1
	s_waitcnt lgkmcnt(0)
	v_mfma_f32_16x16x32_bf16 v[128:131], v[158:161], v[194:197], v[128:131]
	v_mfma_f32_16x16x32_bf16 v[124:127], v[170:173], v[194:197], v[124:127]
	v_mfma_f32_16x16x32_bf16 v[112:115], v[158:161], v[202:205], v[112:115]
	v_mfma_f32_16x16x32_bf16 v[108:111], v[170:173], v[202:205], v[108:111]
	v_mfma_f32_16x16x32_bf16 v[96:99], v[158:161], v[210:213], v[96:99]
	v_mfma_f32_16x16x32_bf16 v[92:95], v[170:173], v[210:213], v[92:95]
	v_mfma_f32_16x16x32_bf16 v[80:83], v[158:161], v[218:221], v[80:83]
	v_mfma_f32_16x16x32_bf16 v[76:79], v[170:173], v[218:221], v[76:79]
	v_mfma_f32_16x16x32_bf16 v[128:131], v[162:165], v[198:201], v[128:131]
	v_mfma_f32_16x16x32_bf16 v[124:127], v[174:177], v[198:201], v[124:127]
	v_mfma_f32_16x16x32_bf16 v[112:115], v[162:165], v[206:209], v[112:115]
	v_mfma_f32_16x16x32_bf16 v[108:111], v[174:177], v[206:209], v[108:111]
	v_mfma_f32_16x16x32_bf16 v[96:99], v[162:165], v[214:217], v[96:99]
	v_mfma_f32_16x16x32_bf16 v[92:95], v[174:177], v[214:217], v[92:95]
	v_mfma_f32_16x16x32_bf16 v[80:83], v[162:165], v[222:225], v[80:83]
	v_mfma_f32_16x16x32_bf16 v[76:79], v[174:177], v[222:225], v[76:79]
	s_setprio 0
	s_setprio 1
	v_mfma_f32_16x16x32_bf16 v[120:123], v[178:181], v[194:197], v[120:123]
	v_mfma_f32_16x16x32_bf16 v[116:119], v[186:189], v[194:197], v[116:119]
	v_mfma_f32_16x16x32_bf16 v[104:107], v[178:181], v[202:205], v[104:107]
	v_mfma_f32_16x16x32_bf16 v[100:103], v[186:189], v[202:205], v[100:103]
	v_mfma_f32_16x16x32_bf16 v[88:91], v[178:181], v[210:213], v[88:91]
	v_mfma_f32_16x16x32_bf16 v[84:87], v[186:189], v[210:213], v[84:87]
	v_mfma_f32_16x16x32_bf16 v[72:75], v[178:181], v[218:221], v[72:75]
	v_mfma_f32_16x16x32_bf16 v[68:71], v[186:189], v[218:221], v[68:71]
	v_mfma_f32_16x16x32_bf16 v[120:123], v[182:185], v[198:201], v[120:123]
	v_mfma_f32_16x16x32_bf16 v[116:119], v[190:193], v[198:201], v[116:119]
	v_mfma_f32_16x16x32_bf16 v[104:107], v[182:185], v[206:209], v[104:107]
	v_mfma_f32_16x16x32_bf16 v[100:103], v[190:193], v[206:209], v[100:103]
	v_mfma_f32_16x16x32_bf16 v[88:91], v[182:185], v[214:217], v[88:91]
	v_mfma_f32_16x16x32_bf16 v[84:87], v[190:193], v[214:217], v[84:87]
	v_mfma_f32_16x16x32_bf16 v[72:75], v[182:185], v[222:225], v[72:75]
	v_mfma_f32_16x16x32_bf16 v[68:71], v[190:193], v[222:225], v[68:71]
	s_setprio 0
	s_barrier
	s_add_i32 s78, s72, s63
	s_mov_b32 m0, s78
	ds_read_b128 v[194:197], v154 offset:16384
	ds_read_b128 v[198:201], v154 offset:17408
	ds_read_b128 v[202:205], v154 offset:18432
	ds_read_b128 v[206:209], v154 offset:19456
	ds_read_b128 v[210:213], v154 offset:20480
	ds_read_b128 v[214:217], v154 offset:21504
	ds_read_b128 v[218:221], v154 offset:22528
	ds_read_b128 v[222:225], v154 offset:23552
	global_load_lds_dwordx4 v132, s[58:59]
	s_add_i32 m0, s78, 0x2000
	s_add_u32 s78, s58, 0x40000
	s_addc_u32 s79, s59, 0
	s_add_i32 s80, s73, s63
	global_load_lds_dwordx4 v134, s[58:59]
	s_mov_b32 m0, s80
	s_nop 0
	global_load_lds_dwordx4 v132, s[78:79]
	s_add_i32 m0, s80, 0x2000
	s_add_u32 vcc_lo, s60, s38
	s_addc_u32 vcc_hi, s61, s39
	global_load_lds_dwordx4 v134, s[78:79]
	s_mov_b32 m0, s53
	s_nop 0
	global_load_lds_dwordx4 v132, s[60:61]
	s_mov_b32 m0, s64
	s_nop 0
	global_load_lds_dwordx4 v134, s[60:61]
	s_waitcnt vmcnt(8)
	s_waitcnt lgkmcnt(0)
	s_barrier
	s_setprio 1
	s_waitcnt lgkmcnt(0)
	v_mfma_f32_16x16x32_bf16 v[64:67], v[158:161], v[194:197], v[64:67]
	v_mfma_f32_16x16x32_bf16 v[60:63], v[170:173], v[194:197], v[60:63]
	v_mfma_f32_16x16x32_bf16 v[48:51], v[158:161], v[202:205], v[48:51]
	v_mfma_f32_16x16x32_bf16 v[44:47], v[170:173], v[202:205], v[44:47]
	v_mfma_f32_16x16x32_bf16 v[32:35], v[158:161], v[210:213], v[32:35]
	v_mfma_f32_16x16x32_bf16 v[28:31], v[170:173], v[210:213], v[28:31]
	v_mfma_f32_16x16x32_bf16 v[16:19], v[158:161], v[218:221], v[16:19]
	v_mfma_f32_16x16x32_bf16 v[12:15], v[170:173], v[218:221], v[12:15]
	v_mfma_f32_16x16x32_bf16 v[64:67], v[162:165], v[198:201], v[64:67]
	v_mfma_f32_16x16x32_bf16 v[60:63], v[174:177], v[198:201], v[60:63]
	v_mfma_f32_16x16x32_bf16 v[48:51], v[162:165], v[206:209], v[48:51]
	v_mfma_f32_16x16x32_bf16 v[44:47], v[174:177], v[206:209], v[44:47]
	v_mfma_f32_16x16x32_bf16 v[32:35], v[162:165], v[214:217], v[32:35]
	v_mfma_f32_16x16x32_bf16 v[28:31], v[174:177], v[214:217], v[28:31]
	v_mfma_f32_16x16x32_bf16 v[16:19], v[162:165], v[222:225], v[16:19]
	v_mfma_f32_16x16x32_bf16 v[12:15], v[174:177], v[222:225], v[12:15]
	s_setprio 0
	s_setprio 1
	v_mfma_f32_16x16x32_bf16 v[56:59], v[178:181], v[194:197], v[56:59]
	v_mfma_f32_16x16x32_bf16 v[52:55], v[186:189], v[194:197], v[52:55]
	v_mfma_f32_16x16x32_bf16 v[40:43], v[178:181], v[202:205], v[40:43]
	v_mfma_f32_16x16x32_bf16 v[36:39], v[186:189], v[202:205], v[36:39]
	v_mfma_f32_16x16x32_bf16 v[24:27], v[178:181], v[210:213], v[24:27]
	v_mfma_f32_16x16x32_bf16 v[20:23], v[186:189], v[210:213], v[20:23]
	v_mfma_f32_16x16x32_bf16 v[8:11], v[178:181], v[218:221], v[8:11]
	v_mfma_f32_16x16x32_bf16 v[2:5], v[186:189], v[218:221], v[4:7]
	v_mfma_f32_16x16x32_bf16 v[56:59], v[182:185], v[198:201], v[56:59]
	v_mfma_f32_16x16x32_bf16 v[52:55], v[190:193], v[198:201], v[52:55]
	v_mfma_f32_16x16x32_bf16 v[40:43], v[182:185], v[206:209], v[40:43]
	v_mfma_f32_16x16x32_bf16 v[36:39], v[190:193], v[206:209], v[36:39]
	v_mfma_f32_16x16x32_bf16 v[24:27], v[182:185], v[214:217], v[24:27]
	v_mfma_f32_16x16x32_bf16 v[20:23], v[190:193], v[214:217], v[20:23]
	v_mfma_f32_16x16x32_bf16 v[8:11], v[182:185], v[222:225], v[8:11]
	v_mfma_f32_16x16x32_bf16 v[2:5], v[190:193], v[222:225], v[2:5]
	s_setprio 0
	s_barrier
	s_add_i32 s78, 0, 0x18000
	v_add_u32_e32 v1, s78, v149
	s_add_i32 s79, 0, 0x1c000
	ds_read_b128 v[158:161], v1
	ds_read_b128 v[162:165], v1 offset:1024
	ds_read_b128 v[170:173], v1 offset:2048
	ds_read_b128 v[174:177], v1 offset:3072
	v_add_u32_e32 v1, s79, v149
	ds_read_b128 v[178:181], v1
	ds_read_b128 v[182:185], v1 offset:1024
	ds_read_b128 v[186:189], v1 offset:2048
	ds_read_b128 v[190:193], v1 offset:3072
	s_add_u32 s60, s60, 0x40000
	s_addc_u32 s61, s61, 0
	s_mov_b32 m0, s65
	ds_read_b128 v[194:197], v154 offset:32768
	ds_read_b128 v[198:201], v154 offset:33792
	ds_read_b128 v[202:205], v154 offset:34816
	ds_read_b128 v[206:209], v154 offset:35840
	ds_read_b128 v[210:213], v154 offset:36864
	ds_read_b128 v[214:217], v154 offset:37888
	ds_read_b128 v[218:221], v154 offset:38912
	ds_read_b128 v[222:225], v154 offset:39936
	global_load_lds_dwordx4 v132, s[60:61]
	s_mov_b32 m0, s66
	s_nop 0
	global_load_lds_dwordx4 v134, s[60:61]
	s_waitcnt vmcnt(8)
	s_waitcnt lgkmcnt(0)
	s_barrier
	s_setprio 1
	s_waitcnt lgkmcnt(0)
	v_mfma_f32_16x16x32_bf16 v[128:131], v[158:161], v[194:197], v[128:131]
	v_mfma_f32_16x16x32_bf16 v[124:127], v[170:173], v[194:197], v[124:127]
	v_mfma_f32_16x16x32_bf16 v[112:115], v[158:161], v[202:205], v[112:115]
	v_mfma_f32_16x16x32_bf16 v[108:111], v[170:173], v[202:205], v[108:111]
	v_mfma_f32_16x16x32_bf16 v[96:99], v[158:161], v[210:213], v[96:99]
	v_mfma_f32_16x16x32_bf16 v[92:95], v[170:173], v[210:213], v[92:95]
	v_mfma_f32_16x16x32_bf16 v[80:83], v[158:161], v[218:221], v[80:83]
	v_mfma_f32_16x16x32_bf16 v[76:79], v[170:173], v[218:221], v[76:79]
	v_mfma_f32_16x16x32_bf16 v[128:131], v[162:165], v[198:201], v[128:131]
	v_mfma_f32_16x16x32_bf16 v[124:127], v[174:177], v[198:201], v[124:127]
	v_mfma_f32_16x16x32_bf16 v[112:115], v[162:165], v[206:209], v[112:115]
	v_mfma_f32_16x16x32_bf16 v[108:111], v[174:177], v[206:209], v[108:111]
	v_mfma_f32_16x16x32_bf16 v[96:99], v[162:165], v[214:217], v[96:99]
	v_mfma_f32_16x16x32_bf16 v[92:95], v[174:177], v[214:217], v[92:95]
	v_mfma_f32_16x16x32_bf16 v[80:83], v[162:165], v[222:225], v[80:83]
	v_mfma_f32_16x16x32_bf16 v[76:79], v[174:177], v[222:225], v[76:79]
	s_setprio 0
	s_setprio 1
	v_mfma_f32_16x16x32_bf16 v[120:123], v[178:181], v[194:197], v[120:123]
	v_mfma_f32_16x16x32_bf16 v[116:119], v[186:189], v[194:197], v[116:119]
	v_mfma_f32_16x16x32_bf16 v[104:107], v[178:181], v[202:205], v[104:107]
	v_mfma_f32_16x16x32_bf16 v[100:103], v[186:189], v[202:205], v[100:103]
	v_mfma_f32_16x16x32_bf16 v[88:91], v[178:181], v[210:213], v[88:91]
	v_mfma_f32_16x16x32_bf16 v[84:87], v[186:189], v[210:213], v[84:87]
	v_mfma_f32_16x16x32_bf16 v[72:75], v[178:181], v[218:221], v[72:75]
	v_mfma_f32_16x16x32_bf16 v[68:71], v[186:189], v[218:221], v[68:71]
	v_mfma_f32_16x16x32_bf16 v[120:123], v[182:185], v[198:201], v[120:123]
	v_mfma_f32_16x16x32_bf16 v[116:119], v[190:193], v[198:201], v[116:119]
	v_mfma_f32_16x16x32_bf16 v[104:107], v[182:185], v[206:209], v[104:107]
	v_mfma_f32_16x16x32_bf16 v[100:103], v[190:193], v[206:209], v[100:103]
	v_mfma_f32_16x16x32_bf16 v[88:91], v[182:185], v[214:217], v[88:91]
	v_mfma_f32_16x16x32_bf16 v[84:87], v[190:193], v[214:217], v[84:87]
	v_mfma_f32_16x16x32_bf16 v[72:75], v[182:185], v[222:225], v[72:75]
	v_mfma_f32_16x16x32_bf16 v[68:71], v[190:193], v[222:225], v[68:71]
	s_setprio 0
	s_barrier
	s_add_i32 s60, s78, s63
	s_add_u32 s98, s58, s38
	s_addc_u32 s99, s59, s39
	s_mov_b32 m0, s60
	ds_read_b128 v[194:197], v154 offset:49152
	ds_read_b128 v[198:201], v154 offset:50176
	ds_read_b128 v[202:205], v154 offset:51200
	ds_read_b128 v[206:209], v154 offset:52224
	ds_read_b128 v[210:213], v154 offset:53248
	ds_read_b128 v[214:217], v154 offset:54272
	ds_read_b128 v[218:221], v154 offset:55296
	ds_read_b128 v[222:225], v154 offset:56320
	global_load_lds_dwordx4 v132, s[98:99]
	s_add_i32 m0, s60, 0x2000
	s_add_u32 s58, s58, 0x40080
	s_addc_u32 s59, s59, 0
	s_add_i32 s60, s79, s63
	global_load_lds_dwordx4 v134, s[98:99]
	s_mov_b32 m0, s60
	s_nop 0
	global_load_lds_dwordx4 v132, s[58:59]
	s_add_i32 m0, s60, 0x2000
	s_nop 0
	global_load_lds_dwordx4 v134, s[58:59]
	s_mov_b32 m0, s67
	s_nop 0
	global_load_lds_dwordx4 v132, vcc
	s_mov_b32 m0, s68
	s_nop 0
	global_load_lds_dwordx4 v134, vcc
	s_waitcnt vmcnt(8)
	s_waitcnt lgkmcnt(0)
	s_barrier
	s_setprio 1
	s_waitcnt lgkmcnt(0)
	v_mfma_f32_16x16x32_bf16 v[64:67], v[158:161], v[194:197], v[64:67]
	v_mfma_f32_16x16x32_bf16 v[60:63], v[170:173], v[194:197], v[60:63]
	v_mfma_f32_16x16x32_bf16 v[48:51], v[158:161], v[202:205], v[48:51]
	v_mfma_f32_16x16x32_bf16 v[44:47], v[170:173], v[202:205], v[44:47]
	v_mfma_f32_16x16x32_bf16 v[32:35], v[158:161], v[210:213], v[32:35]
	v_mfma_f32_16x16x32_bf16 v[28:31], v[170:173], v[210:213], v[28:31]
	v_mfma_f32_16x16x32_bf16 v[16:19], v[158:161], v[218:221], v[16:19]
	v_mfma_f32_16x16x32_bf16 v[12:15], v[170:173], v[218:221], v[12:15]
	v_mfma_f32_16x16x32_bf16 v[64:67], v[162:165], v[198:201], v[64:67]
	v_mfma_f32_16x16x32_bf16 v[60:63], v[174:177], v[198:201], v[60:63]
	v_mfma_f32_16x16x32_bf16 v[48:51], v[162:165], v[206:209], v[48:51]
	v_mfma_f32_16x16x32_bf16 v[44:47], v[174:177], v[206:209], v[44:47]
	v_mfma_f32_16x16x32_bf16 v[32:35], v[162:165], v[214:217], v[32:35]
	v_mfma_f32_16x16x32_bf16 v[28:31], v[174:177], v[214:217], v[28:31]
	v_mfma_f32_16x16x32_bf16 v[16:19], v[162:165], v[222:225], v[16:19]
	v_mfma_f32_16x16x32_bf16 v[12:15], v[174:177], v[222:225], v[12:15]
	s_setprio 0
	s_setprio 1
	v_mfma_f32_16x16x32_bf16 v[56:59], v[178:181], v[194:197], v[56:59]
	v_mfma_f32_16x16x32_bf16 v[52:55], v[186:189], v[194:197], v[52:55]
	v_mfma_f32_16x16x32_bf16 v[40:43], v[178:181], v[202:205], v[40:43]
	v_mfma_f32_16x16x32_bf16 v[36:39], v[186:189], v[202:205], v[36:39]
	v_mfma_f32_16x16x32_bf16 v[24:27], v[178:181], v[210:213], v[24:27]
	v_mfma_f32_16x16x32_bf16 v[20:23], v[186:189], v[210:213], v[20:23]
	v_mfma_f32_16x16x32_bf16 v[6:9], v[178:181], v[218:221], v[8:11]
	v_mfma_f32_16x16x32_bf16 v[2:5], v[186:189], v[218:221], v[2:5]
	v_mfma_f32_16x16x32_bf16 v[56:59], v[182:185], v[198:201], v[56:59]
	v_mfma_f32_16x16x32_bf16 v[52:55], v[190:193], v[198:201], v[52:55]
	v_mfma_f32_16x16x32_bf16 v[40:43], v[182:185], v[206:209], v[40:43]
	v_mfma_f32_16x16x32_bf16 v[36:39], v[190:193], v[206:209], v[36:39]
	v_mfma_f32_16x16x32_bf16 v[24:27], v[182:185], v[214:217], v[24:27]
	v_mfma_f32_16x16x32_bf16 v[20:23], v[190:193], v[214:217], v[20:23]
	v_mfma_f32_16x16x32_bf16 v[8:11], v[182:185], v[222:225], v[6:9]
	v_mfma_f32_16x16x32_bf16 v[4:7], v[190:193], v[222:225], v[2:5]
	s_setprio 0
	s_barrier
	s_add_i32 s77, s77, 2
	s_add_u32 s56, s56, 0x100
	s_addc_u32 s57, s57, 0
	s_cmp_gt_u32 s77, 13
	s_cbranch_scc1 .LBB0_452

.LBB0_627:
	ds_read_b128 v[140:143], v149
	ds_read_b128 v[152:155], v149 offset:1024
	ds_read_b128 v[156:159], v149 offset:2048
	ds_read_b128 v[160:163], v149 offset:3072
	ds_read_b128 v[164:167], v150
	ds_read_b128 v[168:171], v150 offset:1024
	ds_read_b128 v[172:175], v150 offset:2048
	ds_read_b128 v[176:179], v150 offset:3072
	s_add_u32 s34, s28, 0xfff50080
	s_addc_u32 s35, s29, -1
	s_cmp_eq_u32 s55, 40
	s_cselect_b32 s37, s5, s35
	s_cselect_b32 s36, s4, s34
	s_cselect_b32 s35, s27, s54
	s_cselect_b32 s34, s26, s53
	s_add_i32 m0, s39, 0xc000
	ds_read_b128 v[180:183], v151
	ds_read_b128 v[184:187], v151 offset:1024
	ds_read_b128 v[188:191], v151 offset:2048
	ds_read_b128 v[192:195], v151 offset:3072
	ds_read_b128 v[196:199], v151 offset:4096
	ds_read_b128 v[200:203], v151 offset:5120
	ds_read_b128 v[204:207], v151 offset:6144
	ds_read_b128 v[208:211], v151 offset:7168
	global_load_lds_dwordx4 v132, s[28:29]
	s_add_i32 m0, s39, 0xe000
	s_nop 0
	global_load_lds_dwordx4 v134, s[28:29]
	s_waitcnt vmcnt(8)
	s_waitcnt lgkmcnt(0)
	s_barrier
	s_setprio 1
	s_waitcnt lgkmcnt(0)
	v_mfma_f32_16x16x32_bf16 v[124:127], v[140:143], v[180:183], v[124:127]
	v_mfma_f32_16x16x32_bf16 v[120:123], v[156:159], v[180:183], v[120:123]
	v_mfma_f32_16x16x32_bf16 v[112:115], v[140:143], v[188:191], v[112:115]
	v_mfma_f32_16x16x32_bf16 v[104:107], v[156:159], v[188:191], v[104:107]
	v_mfma_f32_16x16x32_bf16 v[96:99], v[140:143], v[196:199], v[96:99]
	v_mfma_f32_16x16x32_bf16 v[88:91], v[156:159], v[196:199], v[88:91]
	v_mfma_f32_16x16x32_bf16 v[80:83], v[140:143], v[204:207], v[80:83]
	v_mfma_f32_16x16x32_bf16 v[72:75], v[156:159], v[204:207], v[72:75]
	v_mfma_f32_16x16x32_bf16 v[124:127], v[152:155], v[184:187], v[124:127]
	v_mfma_f32_16x16x32_bf16 v[120:123], v[160:163], v[184:187], v[120:123]
	v_mfma_f32_16x16x32_bf16 v[112:115], v[152:155], v[192:195], v[112:115]
	v_mfma_f32_16x16x32_bf16 v[104:107], v[160:163], v[192:195], v[104:107]
	v_mfma_f32_16x16x32_bf16 v[96:99], v[152:155], v[200:203], v[96:99]
	v_mfma_f32_16x16x32_bf16 v[88:91], v[160:163], v[200:203], v[88:91]
	v_mfma_f32_16x16x32_bf16 v[80:83], v[152:155], v[208:211], v[80:83]
	v_mfma_f32_16x16x32_bf16 v[72:75], v[160:163], v[208:211], v[72:75]
	s_setprio 0
	s_setprio 1
	v_mfma_f32_16x16x32_bf16 v[116:119], v[164:167], v[180:183], v[116:119]
	v_mfma_f32_16x16x32_bf16 v[108:111], v[172:175], v[180:183], v[108:111]
	v_mfma_f32_16x16x32_bf16 v[100:103], v[164:167], v[188:191], v[100:103]
	v_mfma_f32_16x16x32_bf16 v[92:95], v[172:175], v[188:191], v[92:95]
	v_mfma_f32_16x16x32_bf16 v[84:87], v[164:167], v[196:199], v[84:87]
	v_mfma_f32_16x16x32_bf16 v[76:79], v[172:175], v[196:199], v[76:79]
	v_mfma_f32_16x16x32_bf16 v[68:71], v[164:167], v[204:207], v[68:71]
	v_mfma_f32_16x16x32_bf16 v[64:67], v[172:175], v[204:207], v[64:67]
	v_mfma_f32_16x16x32_bf16 v[116:119], v[168:171], v[184:187], v[116:119]
	v_mfma_f32_16x16x32_bf16 v[108:111], v[176:179], v[184:187], v[108:111]
	v_mfma_f32_16x16x32_bf16 v[100:103], v[168:171], v[192:195], v[100:103]
	v_mfma_f32_16x16x32_bf16 v[92:95], v[176:179], v[192:195], v[92:95]
	v_mfma_f32_16x16x32_bf16 v[84:87], v[168:171], v[200:203], v[84:87]
	v_mfma_f32_16x16x32_bf16 v[76:79], v[176:179], v[200:203], v[76:79]
	v_mfma_f32_16x16x32_bf16 v[68:71], v[168:171], v[208:211], v[68:71]
	v_mfma_f32_16x16x32_bf16 v[64:67], v[176:179], v[208:211], v[64:67]
	s_setprio 0
	s_barrier
	s_add_i32 s56, s47, s38
	s_mov_b32 m0, s56
	ds_read_b128 v[180:183], v151 offset:16384
	ds_read_b128 v[184:187], v151 offset:17408
	ds_read_b128 v[188:191], v151 offset:18432
	ds_read_b128 v[192:195], v151 offset:19456
	ds_read_b128 v[196:199], v151 offset:20480
	ds_read_b128 v[200:203], v151 offset:21504
	ds_read_b128 v[204:207], v151 offset:22528
	ds_read_b128 v[208:211], v151 offset:23552
	global_load_lds_dwordx4 v128, s[34:35]
	s_add_i32 m0, s56, 0x2000
	s_add_u32 s56, s34, 0xb0000
	s_addc_u32 s57, s35, 0
	s_add_i32 s58, s48, s38
	global_load_lds_dwordx4 v130, s[34:35]
	s_mov_b32 m0, s58
	s_nop 0
	global_load_lds_dwordx4 v128, s[56:57]
	s_add_i32 m0, s58, 0x2000
	s_nop 0
	global_load_lds_dwordx4 v130, s[56:57]
	s_add_u32 vcc_lo, s36, s10
	s_addc_u32 vcc_hi, s37, s11
	s_mov_b32 m0, s39
	s_nop 0
	global_load_lds_dwordx4 v128, s[36:37]
	s_mov_b32 m0, s40
	s_nop 0
	global_load_lds_dwordx4 v130, s[36:37]
	s_waitcnt vmcnt(8)
	s_waitcnt lgkmcnt(0)
	s_barrier
	s_setprio 1
	s_waitcnt lgkmcnt(0)
	v_mfma_f32_16x16x32_bf16 v[60:63], v[140:143], v[180:183], v[60:63]
	v_mfma_f32_16x16x32_bf16 v[56:59], v[156:159], v[180:183], v[56:59]
	v_mfma_f32_16x16x32_bf16 v[48:51], v[140:143], v[188:191], v[48:51]
	v_mfma_f32_16x16x32_bf16 v[40:43], v[156:159], v[188:191], v[40:43]
	v_mfma_f32_16x16x32_bf16 v[32:35], v[140:143], v[196:199], v[32:35]
	v_mfma_f32_16x16x32_bf16 v[24:27], v[156:159], v[196:199], v[24:27]
	v_mfma_f32_16x16x32_bf16 v[16:19], v[140:143], v[204:207], v[16:19]
	v_mfma_f32_16x16x32_bf16 v[8:11], v[156:159], v[204:207], v[8:11]
	v_mfma_f32_16x16x32_bf16 v[60:63], v[152:155], v[184:187], v[60:63]
	v_mfma_f32_16x16x32_bf16 v[56:59], v[160:163], v[184:187], v[56:59]
	v_mfma_f32_16x16x32_bf16 v[48:51], v[152:155], v[192:195], v[48:51]
	v_mfma_f32_16x16x32_bf16 v[40:43], v[160:163], v[192:195], v[40:43]
	v_mfma_f32_16x16x32_bf16 v[32:35], v[152:155], v[200:203], v[32:35]
	v_mfma_f32_16x16x32_bf16 v[24:27], v[160:163], v[200:203], v[24:27]
	v_mfma_f32_16x16x32_bf16 v[16:19], v[152:155], v[208:211], v[16:19]
	v_mfma_f32_16x16x32_bf16 v[8:11], v[160:163], v[208:211], v[8:11]
	s_setprio 0
	s_setprio 1
	v_mfma_f32_16x16x32_bf16 v[52:55], v[164:167], v[180:183], v[52:55]
	v_mfma_f32_16x16x32_bf16 v[44:47], v[172:175], v[180:183], v[44:47]
	v_mfma_f32_16x16x32_bf16 v[36:39], v[164:167], v[188:191], v[36:39]
	v_mfma_f32_16x16x32_bf16 v[28:31], v[172:175], v[188:191], v[28:31]
	v_mfma_f32_16x16x32_bf16 v[20:23], v[164:167], v[196:199], v[20:23]
	v_mfma_f32_16x16x32_bf16 v[12:15], v[172:175], v[196:199], v[12:15]
	v_mfma_f32_16x16x32_bf16 v[4:7], v[164:167], v[204:207], v[4:7]
	v_mfma_f32_16x16x32_bf16 v[0:3], v[172:175], v[204:207], v[0:3]
	v_mfma_f32_16x16x32_bf16 v[52:55], v[168:171], v[184:187], v[52:55]
	v_mfma_f32_16x16x32_bf16 v[44:47], v[176:179], v[184:187], v[44:47]
	v_mfma_f32_16x16x32_bf16 v[36:39], v[168:171], v[192:195], v[36:39]
	v_mfma_f32_16x16x32_bf16 v[28:31], v[176:179], v[192:195], v[28:31]
	v_mfma_f32_16x16x32_bf16 v[20:23], v[168:171], v[200:203], v[20:23]
	v_mfma_f32_16x16x32_bf16 v[12:15], v[176:179], v[200:203], v[12:15]
	v_mfma_f32_16x16x32_bf16 v[4:7], v[168:171], v[208:211], v[4:7]
	v_mfma_f32_16x16x32_bf16 v[0:3], v[176:179], v[208:211], v[0:3]
	s_setprio 0
	s_barrier
	s_add_i32 s56, 0, 0x18000
	s_add_i32 s57, 0, 0x1c000
	v_add_u32_e32 v160, s56, v147
	v_add_u32_e32 v176, s57, v147
	ds_read_b128 v[140:143], v160
	ds_read_b128 v[152:155], v160 offset:1024
	ds_read_b128 v[156:159], v160 offset:2048
	ds_read_b128 v[160:163], v160 offset:3072
	ds_read_b128 v[164:167], v176
	ds_read_b128 v[168:171], v176 offset:1024
	ds_read_b128 v[172:175], v176 offset:2048
	ds_read_b128 v[176:179], v176 offset:3072
	s_add_u32 s36, s36, 0xb0000
	s_addc_u32 s37, s37, 0
	s_mov_b32 m0, s41
	ds_read_b128 v[180:183], v151 offset:32768
	ds_read_b128 v[184:187], v151 offset:33792
	ds_read_b128 v[188:191], v151 offset:34816
	ds_read_b128 v[192:195], v151 offset:35840
	ds_read_b128 v[196:199], v151 offset:36864
	ds_read_b128 v[200:203], v151 offset:37888
	ds_read_b128 v[204:207], v151 offset:38912
	ds_read_b128 v[208:211], v151 offset:39936
	global_load_lds_dwordx4 v128, s[36:37]
	s_mov_b32 m0, s42
	s_nop 0
	global_load_lds_dwordx4 v130, s[36:37]
	s_waitcnt vmcnt(8)
	s_waitcnt lgkmcnt(0)
	s_barrier
	s_setprio 1
	s_waitcnt lgkmcnt(0)
	v_mfma_f32_16x16x32_bf16 v[124:127], v[140:143], v[180:183], v[124:127]
	v_mfma_f32_16x16x32_bf16 v[120:123], v[156:159], v[180:183], v[120:123]
	v_mfma_f32_16x16x32_bf16 v[112:115], v[140:143], v[188:191], v[112:115]
	v_mfma_f32_16x16x32_bf16 v[104:107], v[156:159], v[188:191], v[104:107]
	v_mfma_f32_16x16x32_bf16 v[96:99], v[140:143], v[196:199], v[96:99]
	v_mfma_f32_16x16x32_bf16 v[88:91], v[156:159], v[196:199], v[88:91]
	v_mfma_f32_16x16x32_bf16 v[80:83], v[140:143], v[204:207], v[80:83]
	v_mfma_f32_16x16x32_bf16 v[72:75], v[156:159], v[204:207], v[72:75]
	v_mfma_f32_16x16x32_bf16 v[124:127], v[152:155], v[184:187], v[124:127]
	v_mfma_f32_16x16x32_bf16 v[120:123], v[160:163], v[184:187], v[120:123]
	v_mfma_f32_16x16x32_bf16 v[112:115], v[152:155], v[192:195], v[112:115]
	v_mfma_f32_16x16x32_bf16 v[104:107], v[160:163], v[192:195], v[104:107]
	v_mfma_f32_16x16x32_bf16 v[96:99], v[152:155], v[200:203], v[96:99]
	v_mfma_f32_16x16x32_bf16 v[88:91], v[160:163], v[200:203], v[88:91]
	v_mfma_f32_16x16x32_bf16 v[80:83], v[152:155], v[208:211], v[80:83]
	v_mfma_f32_16x16x32_bf16 v[72:75], v[160:163], v[208:211], v[72:75]
	s_setprio 0
	s_setprio 1
	v_mfma_f32_16x16x32_bf16 v[116:119], v[164:167], v[180:183], v[116:119]
	v_mfma_f32_16x16x32_bf16 v[108:111], v[172:175], v[180:183], v[108:111]
	v_mfma_f32_16x16x32_bf16 v[100:103], v[164:167], v[188:191], v[100:103]
	v_mfma_f32_16x16x32_bf16 v[92:95], v[172:175], v[188:191], v[92:95]
	v_mfma_f32_16x16x32_bf16 v[84:87], v[164:167], v[196:199], v[84:87]
	v_mfma_f32_16x16x32_bf16 v[76:79], v[172:175], v[196:199], v[76:79]
	v_mfma_f32_16x16x32_bf16 v[68:71], v[164:167], v[204:207], v[68:71]
	v_mfma_f32_16x16x32_bf16 v[64:67], v[172:175], v[204:207], v[64:67]
	v_mfma_f32_16x16x32_bf16 v[116:119], v[168:171], v[184:187], v[116:119]
	v_mfma_f32_16x16x32_bf16 v[108:111], v[176:179], v[184:187], v[108:111]
	v_mfma_f32_16x16x32_bf16 v[100:103], v[168:171], v[192:195], v[100:103]
	v_mfma_f32_16x16x32_bf16 v[92:95], v[176:179], v[192:195], v[92:95]
	v_mfma_f32_16x16x32_bf16 v[84:87], v[168:171], v[200:203], v[84:87]
	v_mfma_f32_16x16x32_bf16 v[76:79], v[176:179], v[200:203], v[76:79]
	v_mfma_f32_16x16x32_bf16 v[68:71], v[168:171], v[208:211], v[68:71]
	v_mfma_f32_16x16x32_bf16 v[64:67], v[176:179], v[208:211], v[64:67]
	s_setprio 0
	s_barrier
	s_add_i32 s36, s56, s38
	s_add_u32 s98, s34, s10
	s_addc_u32 s99, s35, s11
	s_mov_b32 m0, s36
	ds_read_b128 v[180:183], v151 offset:49152
	ds_read_b128 v[184:187], v151 offset:50176
	ds_read_b128 v[188:191], v151 offset:51200
	ds_read_b128 v[192:195], v151 offset:52224
	ds_read_b128 v[196:199], v151 offset:53248
	ds_read_b128 v[200:203], v151 offset:54272
	ds_read_b128 v[204:207], v151 offset:55296
	ds_read_b128 v[208:211], v151 offset:56320
	global_load_lds_dwordx4 v128, s[98:99]
	s_add_i32 m0, s36, 0x2000
	s_add_u32 s34, s34, 0xb0080
	s_addc_u32 s35, s35, 0
	s_add_i32 s36, s57, s38
	global_load_lds_dwordx4 v130, s[98:99]
	s_mov_b32 m0, s36
	s_nop 0
	global_load_lds_dwordx4 v128, s[34:35]
	s_add_i32 m0, s36, 0x2000
	s_nop 0
	global_load_lds_dwordx4 v130, s[34:35]
	s_mov_b32 m0, s44
	s_nop 0
	global_load_lds_dwordx4 v128, vcc
	s_mov_b32 m0, s45
	s_nop 0
	global_load_lds_dwordx4 v130, vcc
	s_waitcnt vmcnt(8)
	s_waitcnt lgkmcnt(0)
	s_barrier
	s_setprio 1
	s_waitcnt lgkmcnt(0)
	v_mfma_f32_16x16x32_bf16 v[60:63], v[140:143], v[180:183], v[60:63]
	v_mfma_f32_16x16x32_bf16 v[56:59], v[156:159], v[180:183], v[56:59]
	v_mfma_f32_16x16x32_bf16 v[48:51], v[140:143], v[188:191], v[48:51]
	v_mfma_f32_16x16x32_bf16 v[40:43], v[156:159], v[188:191], v[40:43]
	v_mfma_f32_16x16x32_bf16 v[32:35], v[140:143], v[196:199], v[32:35]
	v_mfma_f32_16x16x32_bf16 v[24:27], v[156:159], v[196:199], v[24:27]
	v_mfma_f32_16x16x32_bf16 v[16:19], v[140:143], v[204:207], v[16:19]
	v_mfma_f32_16x16x32_bf16 v[8:11], v[156:159], v[204:207], v[8:11]
	v_mfma_f32_16x16x32_bf16 v[60:63], v[152:155], v[184:187], v[60:63]
	v_mfma_f32_16x16x32_bf16 v[56:59], v[160:163], v[184:187], v[56:59]
	v_mfma_f32_16x16x32_bf16 v[48:51], v[152:155], v[192:195], v[48:51]
	v_mfma_f32_16x16x32_bf16 v[40:43], v[160:163], v[192:195], v[40:43]
	v_mfma_f32_16x16x32_bf16 v[32:35], v[152:155], v[200:203], v[32:35]
	v_mfma_f32_16x16x32_bf16 v[24:27], v[160:163], v[200:203], v[24:27]
	v_mfma_f32_16x16x32_bf16 v[16:19], v[152:155], v[208:211], v[16:19]
	v_mfma_f32_16x16x32_bf16 v[8:11], v[160:163], v[208:211], v[8:11]
	s_setprio 0
	s_setprio 1
	v_mfma_f32_16x16x32_bf16 v[52:55], v[164:167], v[180:183], v[52:55]
	v_mfma_f32_16x16x32_bf16 v[44:47], v[172:175], v[180:183], v[44:47]
	v_mfma_f32_16x16x32_bf16 v[36:39], v[164:167], v[188:191], v[36:39]
	v_mfma_f32_16x16x32_bf16 v[28:31], v[172:175], v[188:191], v[28:31]
	v_mfma_f32_16x16x32_bf16 v[20:23], v[164:167], v[196:199], v[20:23]
	v_mfma_f32_16x16x32_bf16 v[12:15], v[172:175], v[196:199], v[12:15]
	v_mfma_f32_16x16x32_bf16 v[4:7], v[164:167], v[204:207], v[4:7]
	v_mfma_f32_16x16x32_bf16 v[0:3], v[172:175], v[204:207], v[0:3]
	v_mfma_f32_16x16x32_bf16 v[52:55], v[168:171], v[184:187], v[52:55]
	v_mfma_f32_16x16x32_bf16 v[44:47], v[176:179], v[184:187], v[44:47]
	v_mfma_f32_16x16x32_bf16 v[36:39], v[168:171], v[192:195], v[36:39]
	v_mfma_f32_16x16x32_bf16 v[28:31], v[176:179], v[192:195], v[28:31]
	v_mfma_f32_16x16x32_bf16 v[20:23], v[168:171], v[200:203], v[20:23]
	v_mfma_f32_16x16x32_bf16 v[12:15], v[176:179], v[200:203], v[12:15]
	v_mfma_f32_16x16x32_bf16 v[4:7], v[168:171], v[208:211], v[4:7]
	v_mfma_f32_16x16x32_bf16 v[0:3], v[176:179], v[208:211], v[0:3]
	s_setprio 0
	s_barrier
	s_add_i32 s55, s55, 2
	s_add_u32 s28, s28, 0x100
	s_addc_u32 s29, s29, 0
	s_add_u32 s53, s53, 0x100
	s_addc_u32 s54, s54, 0
	s_cmp_gt_u32 s55, 41
	s_cbranch_scc0 .LBB0_627
	s_and_b64 vcc, exec, s[14:15]
	s_cbranch_vccz .LBB0_630
	s_barrier
